# prologue x loop: next row's loads issued a row ahead, head wait leaves previous row's stores in flight
# speedup vs baseline: 1.0075x; 1.0029x over previous
.LBB0_39:
	s_cmpk_gt_i32 s14, 0x3fff
	s_cbranch_scc1 .LBB0_44
	s_ashr_i32 s7, s6, 31
	s_ashr_i32 s8, s0, 31
	s_add_u32 s10, s6, s0
	s_addc_u32 s11, s7, s8
	s_lshl_b64 s[6:7], s[10:11], 6
	v_and_b32_e32 v8, 63, v70
	s_add_u32 s6, s58, s6
	v_lshlrev_b32_e32 v6, 2, v8
	v_mov_b32_e32 v7, 0
	s_addc_u32 s7, s59, s7
	v_lshl_add_u64 v[2:3], s[6:7], 0, v[6:7]
	s_mov_b64 s[6:7], 0x10b00000
	v_lshl_add_u64 v[2:3], v[2:3], 0, s[6:7]
	v_readlane_b32 s6, v251, 26
	v_readlane_b32 s7, v251, 27
	s_mov_b32 s12, s6
	s_ashr_i32 s13, s6, 31
	s_lshl_b64 s[6:7], s[12:13], 6
	s_lshl_b64 s[8:9], s[10:11], 12
	s_add_u32 s8, s60, s8
	v_lshlrev_b32_e32 v6, 4, v8
	s_addc_u32 s9, s61, s9
	v_lshl_add_u64 v[4:5], s[8:9], 0, v[6:7]
	s_mov_b64 s[8:9], 0xc00
	v_lshl_add_u64 v[4:5], v[4:5], 0, s[8:9]
	s_lshl_b64 s[8:9], s[12:13], 12
	s_lshl_b64 s[10:11], s[10:11], 11
	s_add_u32 s10, s58, s10
	v_lshlrev_b32_e32 v6, 3, v8
	s_addc_u32 s11, s59, s11
	v_lshl_add_u64 v[6:7], s[10:11], 0, v[6:7]
	s_mov_b64 s[10:11], 0x5a00400
	v_lshl_add_u64 v[6:7], v[6:7], 0, s[10:11]
	s_mov_b32 s10, s12
	v_writelane_b32 v251, s10, 26
	v_cmp_gt_u32_e32 vcc, 16, v8
	v_cmp_eq_u32_e64 s[4:5], 0, v8
	v_writelane_b32 v251, s11, 27
	s_lshl_b64 s[10:11], s[12:13], 11
	global_load_dwordx4 v[34:37], v[4:5], off offset:-3072
	global_load_dwordx4 v[38:41], v[4:5], off offset:-2048
	global_load_dwordx4 v[42:45], v[4:5], off offset:-1024
	global_load_dwordx4 v[46:49], v[4:5], off
	s_waitcnt vmcnt(0)
	s_branch .LBB0_42

.LBB0_42:
	s_waitcnt vmcnt(5)
	v_mov_b32_e32 v8, v34
	v_mov_b32_e32 v9, v35
	v_mov_b32_e32 v10, v36
	v_mov_b32_e32 v11, v37
	v_mov_b32_e32 v12, v38
	v_mov_b32_e32 v13, v39
	v_mov_b32_e32 v14, v40
	v_mov_b32_e32 v15, v41
	v_mov_b32_e32 v16, v42
	v_mov_b32_e32 v17, v43
	v_mov_b32_e32 v18, v44
	v_mov_b32_e32 v19, v45
	v_mov_b32_e32 v20, v46
	v_mov_b32_e32 v21, v47
	v_mov_b32_e32 v22, v48
	v_mov_b32_e32 v23, v49
	v_readlane_b32 s12, v251, 26
	s_nop 3
	s_add_i32 s13, s14, s12
	s_cmpk_gt_i32 s13, 0x3fff
	s_cbranch_scc1 .Lx_nonext
	v_lshl_add_u64 v[32:33], v[4:5], 0, s[8:9]
	global_load_dwordx4 v[34:37], v[32:33], off offset:-3072
	global_load_dwordx4 v[38:41], v[32:33], off offset:-2048
	global_load_dwordx4 v[42:45], v[32:33], off offset:-1024
	global_load_dwordx4 v[46:49], v[32:33], off
.Lx_nonext:
	v_mul_f32_e32 v24, v9, v9
	v_mul_f32_e32 v25, v11, v11
	v_mul_f32_e32 v26, v13, v13
	v_mul_f32_e32 v27, v15, v15
	v_mul_f32_e32 v28, v17, v17
	v_mul_f32_e32 v29, v19, v19
	v_fmac_f32_e32 v24, v8, v8
	v_fmac_f32_e32 v25, v10, v10
	v_fmac_f32_e32 v26, v12, v12
	v_fmac_f32_e32 v27, v14, v14
	v_mul_f32_e32 v30, v21, v21
	v_mul_f32_e32 v31, v23, v23
	v_fmac_f32_e32 v28, v16, v16
	v_fmac_f32_e32 v29, v18, v18
	v_add_f32_e32 v24, v24, v25
	v_add_f32_e32 v25, v26, v27
	v_fmac_f32_e32 v30, v20, v20
	v_fmac_f32_e32 v31, v22, v22
	v_add_f32_e32 v26, v28, v29
	v_add_f32_e32 v24, v24, v25
	v_add_f32_e32 v27, v30, v31
	v_add_f32_e32 v24, v24, v26
	v_add_f32_e32 v24, v24, v27
	ds_swizzle_b32 v25, v24 offset:swizzle(SWAP,1)
	v_cvt_pk_bf16_f32 v8, v8, v9
	v_cvt_pk_bf16_f32 v9, v10, v11
	v_cvt_pk_bf16_f32 v10, v12, v13
	v_cvt_pk_bf16_f32 v12, v16, v17
	s_waitcnt lgkmcnt(0)
	v_add_f32_e32 v24, v24, v25
	ds_swizzle_b32 v25, v24 offset:swizzle(SWAP,2)
	v_cvt_pk_bf16_f32 v11, v14, v15
	v_cvt_pk_bf16_f32 v13, v18, v19
	global_store_dwordx2 v[6:7], v[8:9], off offset:-1024
	global_store_dwordx2 v[6:7], v[10:11], off offset:-512
	global_store_dwordx2 v[6:7], v[12:13], off
	v_cvt_pk_bf16_f32 v14, v20, v21
	s_waitcnt lgkmcnt(0)
	v_add_f32_e32 v24, v24, v25
	ds_swizzle_b32 v25, v24 offset:swizzle(SWAP,4)
	v_cvt_pk_bf16_f32 v15, v22, v23
	global_store_dwordx2 v[6:7], v[14:15], off offset:512
	s_waitcnt lgkmcnt(0)
	v_add_f32_e32 v24, v24, v25
	ds_swizzle_b32 v25, v24 offset:swizzle(SWAP,8)
	s_waitcnt lgkmcnt(0)
	v_add_f32_e32 v16, v24, v25
	ds_swizzle_b32 v17, v16 offset:swizzle(SWAP,16)
	s_waitcnt lgkmcnt(0)
	v_add_f32_e32 v8, v16, v17
	v_mov_b32_e32 v9, v8
	s_nop 1
	v_permlane32_swap_b32_e32 v8, v9
	s_and_saveexec_b64 s[12:13], vcc
	s_cbranch_execz .LBB0_41
	v_add_f32_e32 v8, v8, v9
	v_cndmask_b32_e64 v8, 0, v8, s[4:5]
	global_store_dword v[2:3], v8, off
	s_branch .LBB0_41
